# P6 final output stores non-temporal (nt), on top of v23
# baseline (speedup 1.0000x reference)
;     __device__ __forceinline__ void fused(f32x4 (&acc)[2][2][4][2], const Unit& u, int wr, int wc, int fr, int fq, PG8_LAS unsigned char* lds, int wid, int lane) const {
;     ...
;         const float qnan = __builtin_nanf("");
; #pragma unroll
;         for (int bj = 0; bj < 2; ++bj) {
;             const f32x4 w0 = *(const f32x4*)(fw + col0 + bj * HALF), w1 = *(const f32x4*)(fw + col0 + bj * HALF + 4);
; #pragma unroll
;             for (int ai = 0; ai < 2; ++ai)
; #pragma unroll
;                 for (int m = 0; m < 4; ++m) { const int r = ai * HALF + wr * 64 + m * 16 + fr; const float sr = S[r]; const size_t off = (size_t)(u.pm * BM + r) * 1024 + col0 + bj * HALF;
;                     f32x4 o0 = acc[ai][bj][m][0] * sr * w0, o1 = acc[ai][bj][m][1] * sr * w1;
;                     if (bad) { o0 = (f32x4){qnan, qnan, qnan, qnan}; o1 = o0; }
;                     *(f32x4*)(out + off) = o0; *(f32x4*)(out + off + 4) = o1; } }
.LBB0_1033:
	s_or_b64 exec, exec, s[2:3]
	v_lshlrev_b64 v[136:137], 2, v[144:145]
	s_waitcnt lgkmcnt(0)
	s_barrier
	v_lshl_add_u64 v[138:139], s[56:57], 0, v[136:137]
	global_load_dwordx4 v[132:135], v[138:139], off
	global_load_dwordx4 v[128:131], v[138:139], off offset:16
	v_lshl_add_u32 v143, v149, 2, 0
	s_waitcnt lgkmcnt(0)
	v_or_b32_e32 v150, v140, v148
	v_add_u32_e32 v140, s16, v149
	v_add_u32_e32 v149, 0x2000, v143
	ds_read_b32 v144, v143 offset:8192
	ds_read_b32 v148, v143 offset:8896
	ds_read2_b32 v[154:155], v149 offset1:16
	v_mov_b32_e32 v145, 0x7fc00000
	v_ashrrev_i32_e32 v141, 31, v140
	v_add_u32_e32 v142, 16, v140
	ds_read2_b32 v[156:157], v149 offset0:16 offset1:32
	v_lshlrev_b64 v[152:153], 12, v[140:141]
	v_ashrrev_i32_e32 v143, 31, v142
	s_waitcnt lgkmcnt(3)
	v_pk_mul_f32 v[58:59], v[58:59], v[144:145] op_sel_hi:[1,0]
	v_pk_mul_f32 v[56:57], v[56:57], v[144:145] op_sel_hi:[1,0]
	v_pk_mul_f32 v[62:63], v[62:63], v[144:145] op_sel_hi:[1,0]
	v_pk_mul_f32 v[60:61], v[60:61], v[144:145] op_sel_hi:[1,0]
	s_waitcnt lgkmcnt(1)
	v_mov_b32_e32 v144, v155
	v_lshl_add_u64 v[158:159], s[58:59], 0, v[152:153]
	v_lshlrev_b64 v[142:143], 12, v[142:143]
	v_pk_mul_f32 v[86:87], v[86:87], v[144:145] op_sel_hi:[1,0]
	v_pk_mul_f32 v[84:85], v[84:85], v[144:145] op_sel_hi:[1,0]
	v_pk_mul_f32 v[90:91], v[90:91], v[144:145] op_sel_hi:[1,0]
	v_pk_mul_f32 v[88:89], v[88:89], v[144:145] op_sel_hi:[1,0]
	v_cmp_ne_u32_e32 vcc, 0, v150
	v_lshl_add_u64 v[158:159], v[158:159], 0, v[136:137]
	v_lshl_add_u64 v[160:161], s[58:59], 0, v[142:143]
	v_add_u32_e32 v146, 32, v140
	v_lshl_add_u64 v[160:161], v[160:161], 0, v[136:137]
	v_ashrrev_i32_e32 v147, 31, v146
	s_waitcnt lgkmcnt(0)
	v_mov_b32_e32 v164, v157
	v_lshlrev_b64 v[146:147], 12, v[146:147]
	v_pk_mul_f32 v[106:107], v[106:107], v[164:165] op_sel_hi:[1,0]
	v_pk_mul_f32 v[104:105], v[104:105], v[164:165] op_sel_hi:[1,0]
	v_lshl_add_u64 v[162:163], s[58:59], 0, v[146:147]
	v_pk_mul_f32 v[110:111], v[110:111], v[164:165] op_sel_hi:[1,0]
	v_pk_mul_f32 v[108:109], v[108:109], v[164:165] op_sel_hi:[1,0]
	v_lshl_add_u64 v[162:163], v[162:163], 0, v[136:137]
	v_pk_mul_f32 v[2:3], v[2:3], v[148:149] op_sel_hi:[1,0]
	v_pk_mul_f32 v[0:1], v[0:1], v[148:149] op_sel_hi:[1,0]
	v_pk_mul_f32 v[6:7], v[6:7], v[148:149] op_sel_hi:[1,0]
	v_pk_mul_f32 v[4:5], v[4:5], v[148:149] op_sel_hi:[1,0]
	s_waitcnt vmcnt(1)
	v_pk_mul_f32 v[56:57], v[132:133], v[56:57]
	v_pk_mul_f32 v[58:59], v[134:135], v[58:59]
	s_waitcnt vmcnt(0)
	v_pk_mul_f32 v[60:61], v[128:129], v[60:61]
	v_pk_mul_f32 v[62:63], v[130:131], v[62:63]
	v_pk_mul_f32 v[84:85], v[132:133], v[84:85]
	v_pk_mul_f32 v[86:87], v[134:135], v[86:87]
	v_pk_mul_f32 v[88:89], v[128:129], v[88:89]
	v_pk_mul_f32 v[90:91], v[130:131], v[90:91]
	v_cndmask_b32_e32 v59, v59, v145, vcc
	v_cndmask_b32_e32 v58, v58, v145, vcc
	v_cndmask_b32_e32 v57, v57, v145, vcc
	v_cndmask_b32_e32 v56, v56, v145, vcc
	v_cndmask_b32_e32 v63, v63, v145, vcc
	v_cndmask_b32_e32 v62, v62, v145, vcc
	v_cndmask_b32_e32 v61, v61, v145, vcc
	v_cndmask_b32_e32 v60, v60, v145, vcc
	v_cndmask_b32_e32 v87, v87, v145, vcc
	v_cndmask_b32_e32 v86, v86, v145, vcc
	v_cndmask_b32_e32 v85, v85, v145, vcc
	v_cndmask_b32_e32 v84, v84, v145, vcc
	v_cndmask_b32_e32 v91, v91, v145, vcc
	v_cndmask_b32_e32 v90, v90, v145, vcc
	v_cndmask_b32_e32 v89, v89, v145, vcc
	v_cndmask_b32_e32 v88, v88, v145, vcc
	global_store_dwordx4 v[158:159], v[56:59], off nt
	global_store_dwordx4 v[158:159], v[60:63], off offset:16 nt
	global_store_dwordx4 v[160:161], v[84:87], off nt
	global_store_dwordx4 v[160:161], v[88:91], off offset:16 nt
	ds_read2_b32 v[84:85], v149 offset0:32 offset1:48
	v_pk_mul_f32 v[104:105], v[132:133], v[104:105]
	v_pk_mul_f32 v[106:107], v[134:135], v[106:107]
	v_pk_mul_f32 v[108:109], v[128:129], v[108:109]
	v_pk_mul_f32 v[110:111], v[130:131], v[110:111]
	v_cndmask_b32_e32 v107, v107, v145, vcc
	v_cndmask_b32_e32 v106, v106, v145, vcc
	v_cndmask_b32_e32 v105, v105, v145, vcc
	v_cndmask_b32_e32 v104, v104, v145, vcc
	v_cndmask_b32_e32 v111, v111, v145, vcc
	v_cndmask_b32_e32 v110, v110, v145, vcc
	v_cndmask_b32_e32 v109, v109, v145, vcc
	v_cndmask_b32_e32 v108, v108, v145, vcc
	global_store_dwordx4 v[162:163], v[104:107], off nt
	global_store_dwordx4 v[162:163], v[108:111], off offset:16 nt
	v_add_u32_e32 v86, 48, v140
	s_waitcnt lgkmcnt(0)
	v_mov_b32_e32 v56, v85
	ds_read2_b32 v[90:91], v149 offset0:48 offset1:128
	v_ashrrev_i32_e32 v87, 31, v86
	v_pk_mul_f32 v[58:59], v[126:127], v[56:57] op_sel_hi:[1,0]
	v_pk_mul_f32 v[60:61], v[124:125], v[56:57] op_sel_hi:[1,0]
	v_pk_mul_f32 v[62:63], v[122:123], v[56:57] op_sel_hi:[1,0]
	v_pk_mul_f32 v[56:57], v[120:121], v[56:57] op_sel_hi:[1,0]
	v_pk_mul_f32 v[60:61], v[132:133], v[60:61]
	v_pk_mul_f32 v[88:89], v[128:129], v[56:57]
	v_lshlrev_b64 v[86:87], 12, v[86:87]
	v_pk_mul_f32 v[58:59], v[134:135], v[58:59]
	v_cndmask_b32_e32 v57, v61, v145, vcc
	v_cndmask_b32_e32 v56, v60, v145, vcc
	v_cndmask_b32_e32 v61, v89, v145, vcc
	v_cndmask_b32_e32 v60, v88, v145, vcc
	v_lshl_add_u64 v[88:89], s[58:59], 0, v[86:87]
	v_pk_mul_f32 v[62:63], v[130:131], v[62:63]
	v_cndmask_b32_e32 v59, v59, v145, vcc
	v_cndmask_b32_e32 v58, v58, v145, vcc
	v_lshl_add_u64 v[88:89], v[88:89], 0, v[136:137]
	v_cndmask_b32_e32 v63, v63, v145, vcc
	v_cndmask_b32_e32 v62, v62, v145, vcc
	global_store_dwordx4 v[88:89], v[56:59], off nt
	global_store_dwordx4 v[88:89], v[60:63], off offset:16 nt
	v_add_u32_e32 v88, 0x80, v140
	s_waitcnt lgkmcnt(0)
;     __device__ __forceinline__ void fused(f32x4 (&acc)[2][2][4][2], const Unit& u, int wr, int wc, int fr, int fq, PG8_LAS unsigned char* lds, int wid, int lane) const {
;     ...
;         for (int bj = 0; bj < 2; ++bj) {
;             const f32x4 w0 = *(const f32x4*)(fw + col0 + bj * HALF), w1 = *(const f32x4*)(fw + col0 + bj * HALF + 4);
; #pragma unroll
;             for (int ai = 0; ai < 2; ++ai)
; #pragma unroll
;                 for (int m = 0; m < 4; ++m) { const int r = ai * HALF + wr * 64 + m * 16 + fr; const float sr = S[r]; const size_t off = (size_t)(u.pm * BM + r) * 1024 + col0 + bj * HALF;
;                     f32x4 o0 = acc[ai][bj][m][0] * sr * w0, o1 = acc[ai][bj][m][1] * sr * w1;
;                     if (bad) { o0 = (f32x4){qnan, qnan, qnan, qnan}; o1 = o0; }
;                     *(f32x4*)(out + off) = o0; *(f32x4*)(out + off + 4) = o1; } }
	v_mov_b32_e32 v56, v91
	v_pk_mul_f32 v[58:59], v[94:95], v[56:57] op_sel_hi:[1,0]
	v_pk_mul_f32 v[60:61], v[92:93], v[56:57] op_sel_hi:[1,0]
	v_pk_mul_f32 v[62:63], v[82:83], v[56:57] op_sel_hi:[1,0]
	v_pk_mul_f32 v[56:57], v[80:81], v[56:57] op_sel_hi:[1,0]
	v_ashrrev_i32_e32 v89, 31, v88
	v_pk_mul_f32 v[60:61], v[132:133], v[60:61]
	v_pk_mul_f32 v[80:81], v[128:129], v[56:57]
	v_cndmask_b32_e32 v57, v61, v145, vcc
	v_cndmask_b32_e32 v56, v60, v145, vcc
	v_cndmask_b32_e32 v61, v81, v145, vcc
	v_cndmask_b32_e32 v60, v80, v145, vcc
	v_lshlrev_b64 v[80:81], 12, v[88:89]
	ds_read2_b32 v[88:89], v149 offset0:128 offset1:144
	v_pk_mul_f32 v[58:59], v[134:135], v[58:59]
	v_lshl_add_u64 v[82:83], s[58:59], 0, v[80:81]
	v_pk_mul_f32 v[62:63], v[130:131], v[62:63]
	v_cndmask_b32_e32 v59, v59, v145, vcc
	v_cndmask_b32_e32 v58, v58, v145, vcc
	v_lshl_add_u64 v[82:83], v[82:83], 0, v[136:137]
	v_cndmask_b32_e32 v63, v63, v145, vcc
	v_cndmask_b32_e32 v62, v62, v145, vcc
	global_store_dwordx4 v[82:83], v[56:59], off nt
	global_store_dwordx4 v[82:83], v[60:63], off offset:16 nt
	s_waitcnt lgkmcnt(0)
	v_mov_b32_e32 v58, v89
	v_pk_mul_f32 v[54:55], v[54:55], v[58:59] op_sel_hi:[1,0]
	v_pk_mul_f32 v[50:51], v[50:51], v[58:59] op_sel_hi:[1,0]
	v_pk_mul_f32 v[54:55], v[134:135], v[54:55]
	v_pk_mul_f32 v[60:61], v[130:131], v[50:51]
	v_add_u32_e32 v56, 0x90, v140
	v_cndmask_b32_e32 v51, v55, v145, vcc
	v_cndmask_b32_e32 v50, v54, v145, vcc
	v_cndmask_b32_e32 v55, v61, v145, vcc
	v_cndmask_b32_e32 v54, v60, v145, vcc
	ds_read2_b32 v[60:61], v149 offset0:144 offset1:160
	v_ashrrev_i32_e32 v57, 31, v56
	v_pk_mul_f32 v[52:53], v[52:53], v[58:59] op_sel_hi:[1,0]
	v_pk_mul_f32 v[48:49], v[48:49], v[58:59] op_sel_hi:[1,0]
	v_pk_mul_f32 v[52:53], v[132:133], v[52:53]
	v_pk_mul_f32 v[58:59], v[128:129], v[48:49]
	v_lshlrev_b64 v[56:57], 12, v[56:57]
	v_cndmask_b32_e32 v49, v53, v145, vcc
	v_cndmask_b32_e32 v48, v52, v145, vcc
	v_cndmask_b32_e32 v53, v59, v145, vcc
	v_cndmask_b32_e32 v52, v58, v145, vcc
	v_lshl_add_u64 v[58:59], s[58:59], 0, v[56:57]
	v_lshl_add_u64 v[58:59], v[58:59], 0, v[136:137]
	global_store_dwordx4 v[58:59], v[48:51], off nt
	global_store_dwordx4 v[58:59], v[52:55], off offset:16 nt
	s_waitcnt lgkmcnt(0)
	v_mov_b32_e32 v50, v61
	v_pk_mul_f32 v[30:31], v[30:31], v[50:51] op_sel_hi:[1,0]
	v_pk_mul_f32 v[26:27], v[26:27], v[50:51] op_sel_hi:[1,0]
	v_add_u32_e32 v48, 0xa0, v140
	v_pk_mul_f32 v[30:31], v[134:135], v[30:31]
	v_pk_mul_f32 v[52:53], v[130:131], v[26:27]
	v_ashrrev_i32_e32 v49, 31, v48
	v_pk_mul_f32 v[28:29], v[28:29], v[50:51] op_sel_hi:[1,0]
	v_pk_mul_f32 v[24:25], v[24:25], v[50:51] op_sel_hi:[1,0]
	v_cndmask_b32_e32 v27, v31, v145, vcc
	v_cndmask_b32_e32 v26, v30, v145, vcc
	v_cndmask_b32_e32 v31, v53, v145, vcc
	v_cndmask_b32_e32 v30, v52, v145, vcc
	ds_read2_b32 v[52:53], v149 offset0:160 offset1:176
	v_pk_mul_f32 v[28:29], v[132:133], v[28:29]
	v_pk_mul_f32 v[50:51], v[128:129], v[24:25]
	v_lshlrev_b64 v[48:49], 12, v[48:49]
	v_cndmask_b32_e32 v25, v29, v145, vcc
	v_cndmask_b32_e32 v24, v28, v145, vcc
	v_cndmask_b32_e32 v29, v51, v145, vcc
	v_cndmask_b32_e32 v28, v50, v145, vcc
	v_lshl_add_u64 v[50:51], s[58:59], 0, v[48:49]
	v_lshl_add_u64 v[50:51], v[50:51], 0, v[136:137]
	global_store_dwordx4 v[50:51], v[24:27], off nt
	global_store_dwordx4 v[50:51], v[28:31], off offset:16 nt
	s_waitcnt lgkmcnt(0)
	v_pk_mul_f32 v[18:19], v[18:19], v[52:53] op_sel_hi:[1,0]
	v_add_u32_e32 v24, 0xb0, v140
	v_ashrrev_i32_e32 v25, 31, v24
	v_mov_b32_e32 v26, v53
	v_pk_mul_f32 v[14:15], v[14:15], v[26:27] op_sel_hi:[1,0]
	v_pk_mul_f32 v[12:13], v[12:13], v[26:27] op_sel_hi:[1,0]
	v_lshlrev_b64 v[50:51], 12, v[24:25]
	v_pk_mul_f32 v[12:13], v[132:133], v[12:13]
	v_pk_mul_f32 v[14:15], v[134:135], v[14:15]
	v_pk_mul_f32 v[10:11], v[10:11], v[26:27] op_sel_hi:[1,0]
	v_pk_mul_f32 v[8:9], v[8:9], v[26:27] op_sel_hi:[1,0]
	v_lshl_add_u64 v[24:25], s[58:59], 0, v[50:51]
	v_pk_mul_f32 v[26:27], v[128:129], v[8:9]
	v_pk_mul_f32 v[28:29], v[130:131], v[10:11]
	v_cndmask_b32_e32 v11, v15, v145, vcc
	v_cndmask_b32_e32 v10, v14, v145, vcc
	v_cndmask_b32_e32 v9, v13, v145, vcc
	v_cndmask_b32_e32 v8, v12, v145, vcc
	v_lshl_add_u64 v[24:25], v[24:25], 0, v[136:137]
	v_cndmask_b32_e32 v15, v29, v145, vcc
	v_cndmask_b32_e32 v14, v28, v145, vcc
	v_cndmask_b32_e32 v13, v27, v145, vcc
	v_cndmask_b32_e32 v12, v26, v145, vcc
	global_store_dwordx4 v[24:25], v[8:11], off nt
	global_store_dwordx4 v[24:25], v[12:15], off offset:16 nt
	global_load_dwordx4 v[8:11], v[138:139], off offset:512
	s_nop 0
	global_load_dwordx4 v[12:15], v[138:139], off offset:528
	v_pk_mul_f32 v[24:25], v[34:35], v[154:155] op_sel_hi:[1,0]
	v_pk_mul_f32 v[26:27], v[32:33], v[154:155] op_sel_hi:[1,0]
	v_pk_mul_f32 v[30:31], v[36:37], v[154:155] op_sel_hi:[1,0]
	v_pk_mul_f32 v[16:17], v[16:17], v[52:53] op_sel_hi:[1,0]
	v_pk_mul_f32 v[22:23], v[22:23], v[52:53] op_sel_hi:[1,0]
	v_pk_mul_f32 v[20:21], v[20:21], v[52:53] op_sel_hi:[1,0]
	s_waitcnt vmcnt(1)
	v_pk_mul_f32 v[28:29], v[8:9], v[26:27]
	v_pk_mul_f32 v[24:25], v[10:11], v[24:25]
	v_pk_mul_f32 v[26:27], v[38:39], v[154:155] op_sel_hi:[1,0]
	s_waitcnt vmcnt(0)
;     __device__ __forceinline__ void fused(f32x4 (&acc)[2][2][4][2], const Unit& u, int wr, int wc, int fr, int fq, PG8_LAS unsigned char* lds, int wid, int lane) const {
;     ...
;         for (int bj = 0; bj < 2; ++bj) {
;             const f32x4 w0 = *(const f32x4*)(fw + col0 + bj * HALF), w1 = *(const f32x4*)(fw + col0 + bj * HALF + 4);
; #pragma unroll
;             for (int ai = 0; ai < 2; ++ai)
; #pragma unroll
;                 for (int m = 0; m < 4; ++m) { const int r = ai * HALF + wr * 64 + m * 16 + fr; const float sr = S[r]; const size_t off = (size_t)(u.pm * BM + r) * 1024 + col0 + bj * HALF;
;                     f32x4 o0 = acc[ai][bj][m][0] * sr * w0, o1 = acc[ai][bj][m][1] * sr * w1;
;                     if (bad) { o0 = (f32x4){qnan, qnan, qnan, qnan}; o1 = o0; }
;                     *(f32x4*)(out + off) = o0; *(f32x4*)(out + off + 4) = o1; } }
	v_pk_mul_f32 v[32:33], v[12:13], v[30:31]
	v_pk_mul_f32 v[30:31], v[14:15], v[26:27]
	v_cndmask_b32_e32 v27, v25, v145, vcc
	v_cndmask_b32_e32 v26, v24, v145, vcc
	v_cndmask_b32_e32 v25, v29, v145, vcc
	v_cndmask_b32_e32 v24, v28, v145, vcc
	v_cndmask_b32_e32 v29, v33, v145, vcc
	v_cndmask_b32_e32 v28, v32, v145, vcc
	v_lshl_add_u64 v[32:33], s[58:59], 0, v[136:137]
	v_cndmask_b32_e32 v31, v31, v145, vcc
	v_cndmask_b32_e32 v30, v30, v145, vcc
	v_lshl_add_u64 v[34:35], v[32:33], 0, v[152:153]
	global_store_dwordx4 v[34:35], v[24:27], off offset:512 nt
	global_store_dwordx4 v[34:35], v[28:31], off offset:528 nt
	v_pk_mul_f32 v[16:17], v[8:9], v[16:17]
	v_pk_mul_f32 v[24:25], v[66:67], v[156:157] op_sel_hi:[1,0]
	v_pk_mul_f32 v[26:27], v[64:65], v[156:157] op_sel_hi:[1,0]
	v_pk_mul_f32 v[30:31], v[68:69], v[156:157] op_sel_hi:[1,0]
	v_pk_mul_f32 v[28:29], v[8:9], v[26:27]
	v_pk_mul_f32 v[24:25], v[10:11], v[24:25]
	v_pk_mul_f32 v[26:27], v[70:71], v[156:157] op_sel_hi:[1,0]
	v_pk_mul_f32 v[34:35], v[12:13], v[30:31]
	v_pk_mul_f32 v[30:31], v[14:15], v[26:27]
	v_cndmask_b32_e32 v27, v25, v145, vcc
	v_cndmask_b32_e32 v26, v24, v145, vcc
	v_cndmask_b32_e32 v25, v29, v145, vcc
	v_cndmask_b32_e32 v24, v28, v145, vcc
	v_cndmask_b32_e32 v29, v35, v145, vcc
	v_cndmask_b32_e32 v28, v34, v145, vcc
	v_lshl_add_u64 v[34:35], v[32:33], 0, v[142:143]
	v_cndmask_b32_e32 v31, v31, v145, vcc
	v_cndmask_b32_e32 v30, v30, v145, vcc
	global_store_dwordx4 v[34:35], v[24:27], off offset:512 nt
	global_store_dwordx4 v[34:35], v[28:31], off offset:528 nt
	v_pk_mul_f32 v[18:19], v[10:11], v[18:19]
	v_pk_mul_f32 v[26:27], v[96:97], v[84:85] op_sel_hi:[1,0]
	v_pk_mul_f32 v[24:25], v[98:99], v[84:85] op_sel_hi:[1,0]
	v_pk_mul_f32 v[28:29], v[8:9], v[26:27]
	v_pk_mul_f32 v[26:27], v[102:103], v[84:85] op_sel_hi:[1,0]
	v_pk_mul_f32 v[30:31], v[100:101], v[84:85] op_sel_hi:[1,0]
	v_pk_mul_f32 v[24:25], v[10:11], v[24:25]
	v_pk_mul_f32 v[34:35], v[12:13], v[30:31]
	v_pk_mul_f32 v[30:31], v[14:15], v[26:27]
	v_cndmask_b32_e32 v27, v25, v145, vcc
	v_cndmask_b32_e32 v26, v24, v145, vcc
	v_cndmask_b32_e32 v25, v29, v145, vcc
	v_cndmask_b32_e32 v24, v28, v145, vcc
	v_cndmask_b32_e32 v31, v31, v145, vcc
	v_cndmask_b32_e32 v30, v30, v145, vcc
	v_cndmask_b32_e32 v29, v35, v145, vcc
	v_cndmask_b32_e32 v28, v34, v145, vcc
	v_lshl_add_u64 v[34:35], v[32:33], 0, v[146:147]
	global_store_dwordx4 v[34:35], v[24:27], off offset:512 nt
	global_store_dwordx4 v[34:35], v[28:31], off offset:528 nt
	v_pk_mul_f32 v[0:1], v[8:9], v[0:1]
	v_pk_mul_f32 v[24:25], v[114:115], v[90:91] op_sel_hi:[1,0]
	v_pk_mul_f32 v[26:27], v[112:113], v[90:91] op_sel_hi:[1,0]
	v_pk_mul_f32 v[30:31], v[116:117], v[90:91] op_sel_hi:[1,0]
	v_pk_mul_f32 v[28:29], v[8:9], v[26:27]
	v_pk_mul_f32 v[24:25], v[10:11], v[24:25]
	v_pk_mul_f32 v[26:27], v[118:119], v[90:91] op_sel_hi:[1,0]
	v_pk_mul_f32 v[34:35], v[12:13], v[30:31]
	v_pk_mul_f32 v[30:31], v[14:15], v[26:27]
	v_cndmask_b32_e32 v27, v25, v145, vcc
	v_cndmask_b32_e32 v26, v24, v145, vcc
	v_cndmask_b32_e32 v25, v29, v145, vcc
	v_cndmask_b32_e32 v24, v28, v145, vcc
	v_cndmask_b32_e32 v29, v35, v145, vcc
	v_cndmask_b32_e32 v28, v34, v145, vcc
	v_lshl_add_u64 v[34:35], v[32:33], 0, v[86:87]
	v_cndmask_b32_e32 v31, v31, v145, vcc
	v_cndmask_b32_e32 v30, v30, v145, vcc
	global_store_dwordx4 v[34:35], v[24:27], off offset:512 nt
	global_store_dwordx4 v[34:35], v[28:31], off offset:528 nt
	v_pk_mul_f32 v[2:3], v[10:11], v[2:3]
	v_pk_mul_f32 v[26:27], v[72:73], v[88:89] op_sel_hi:[1,0]
	v_pk_mul_f32 v[24:25], v[74:75], v[88:89] op_sel_hi:[1,0]
	v_pk_mul_f32 v[28:29], v[8:9], v[26:27]
	v_pk_mul_f32 v[26:27], v[78:79], v[88:89] op_sel_hi:[1,0]
	v_pk_mul_f32 v[30:31], v[76:77], v[88:89] op_sel_hi:[1,0]
	v_pk_mul_f32 v[24:25], v[10:11], v[24:25]
	v_pk_mul_f32 v[34:35], v[12:13], v[30:31]
	v_pk_mul_f32 v[30:31], v[14:15], v[26:27]
	v_cndmask_b32_e32 v27, v25, v145, vcc
	v_cndmask_b32_e32 v26, v24, v145, vcc
	v_cndmask_b32_e32 v25, v29, v145, vcc
	v_cndmask_b32_e32 v24, v28, v145, vcc
	v_cndmask_b32_e32 v31, v31, v145, vcc
	v_cndmask_b32_e32 v30, v30, v145, vcc
	v_cndmask_b32_e32 v29, v35, v145, vcc
	v_cndmask_b32_e32 v28, v34, v145, vcc
	v_lshl_add_u64 v[34:35], v[32:33], 0, v[80:81]
	global_store_dwordx4 v[34:35], v[24:27], off offset:512 nt
	global_store_dwordx4 v[34:35], v[28:31], off offset:528 nt
	v_pk_mul_f32 v[20:21], v[12:13], v[20:21]
	v_pk_mul_f32 v[24:25], v[42:43], v[60:61] op_sel_hi:[1,0]
	v_pk_mul_f32 v[26:27], v[40:41], v[60:61] op_sel_hi:[1,0]
	v_pk_mul_f32 v[30:31], v[44:45], v[60:61] op_sel_hi:[1,0]
	v_pk_mul_f32 v[28:29], v[8:9], v[26:27]
	v_pk_mul_f32 v[24:25], v[10:11], v[24:25]
	v_pk_mul_f32 v[26:27], v[46:47], v[60:61] op_sel_hi:[1,0]
	v_pk_mul_f32 v[34:35], v[12:13], v[30:31]
	v_pk_mul_f32 v[30:31], v[14:15], v[26:27]
	v_cndmask_b32_e32 v27, v25, v145, vcc
	v_cndmask_b32_e32 v26, v24, v145, vcc
	v_cndmask_b32_e32 v25, v29, v145, vcc
	v_cndmask_b32_e32 v24, v28, v145, vcc
	v_cndmask_b32_e32 v29, v35, v145, vcc
	v_cndmask_b32_e32 v28, v34, v145, vcc
	v_lshl_add_u64 v[34:35], v[32:33], 0, v[56:57]
	v_cndmask_b32_e32 v31, v31, v145, vcc
	v_cndmask_b32_e32 v30, v30, v145, vcc
	global_store_dwordx4 v[34:35], v[24:27], off offset:512 nt
	global_store_dwordx4 v[34:35], v[28:31], off offset:528 nt
	v_pk_mul_f32 v[22:23], v[14:15], v[22:23]
	v_cndmask_b32_e32 v19, v19, v145, vcc
	v_cndmask_b32_e32 v18, v18, v145, vcc
	v_cndmask_b32_e32 v17, v17, v145, vcc
	v_cndmask_b32_e32 v16, v16, v145, vcc
	v_lshl_add_u64 v[24:25], v[32:33], 0, v[48:49]
	v_pk_mul_f32 v[4:5], v[12:13], v[4:5]
	v_pk_mul_f32 v[6:7], v[14:15], v[6:7]
	v_cndmask_b32_e32 v3, v3, v145, vcc
	v_cndmask_b32_e32 v2, v2, v145, vcc
	v_cndmask_b32_e32 v1, v1, v145, vcc
	v_cndmask_b32_e32 v0, v0, v145, vcc
	v_lshl_add_u64 v[8:9], v[32:33], 0, v[50:51]
	v_cndmask_b32_e32 v23, v23, v145, vcc
	v_cndmask_b32_e32 v22, v22, v145, vcc
	v_cndmask_b32_e32 v21, v21, v145, vcc
	v_cndmask_b32_e32 v20, v20, v145, vcc
	global_store_dwordx4 v[24:25], v[16:19], off offset:512 nt
	global_store_dwordx4 v[24:25], v[20:23], off offset:528 nt
	v_cndmask_b32_e32 v7, v7, v145, vcc
	v_cndmask_b32_e32 v6, v6, v145, vcc
	v_cndmask_b32_e32 v5, v5, v145, vcc
	v_cndmask_b32_e32 v4, v4, v145, vcc
	global_store_dwordx4 v[8:9], v[0:3], off offset:512 nt
	global_store_dwordx4 v[8:9], v[4:7], off offset:528 nt
